# v49 plus sample-attention unit header: seven of the eight serial global_load->wait->ds_write rounds of the Q image issued together (2 round trips instead of 8)
# baseline (speedup 1.0000x reference)
; __device__ __forceinline__ int lau_v(int x) { asm volatile("" : "+v"(x)); return x; }
; __device__ __forceinline__ void unit(const bf16_t* __restrict__ Qs_bh  , const float* __restrict__ Clat  , const float* __restrict__ Ckpe  , const bf16_t* __restrict__ Kn  , ...
;   const int tid = wid * 64 + lane, qh = wid >> 2, cq = wid & 3, l15 = lane & 15, g4 = lane >> 4, r32 = lane & 31, hi = lane >> 5;
;   float* wsf = (float*)(lds + WSCR) + wid * 64; float* li_l = wsf; float* al_l = wsf + 32;
; #pragma unroll
;   for (int j = 0; j < 8; ++j) { const int c = lau_v(tid) + 512 * j, q = c >> 6, ch = c & 63;
;     *(bf16x8*)(lds + QIMG + (ch >> 4) * 16384 + off_b(q, ch & 15)) = *reinterpret_cast<const bf16x8*>(Qs_bh + (size_t)q * (HEADS * KVW) + ch * 8); }
.LBB0_1550:
	s_ashr_i32 s6, s44, 3
	s_ashr_i32 s7, s6, 31
	s_and_b32 s45, s44, 7
	s_lshl_b64 s[2:3], s[6:7], 9
	s_or_b32 s2, s2, s45
	s_mulk_i32 s3, 0x480
	s_mul_hi_u32 s14, s2, 0x480
	s_lshl_b64 s[0:1], s[6:7], 6
	s_add_i32 s3, s14, s3
	s_mulk_i32 s2, 0x480
	s_add_u32 s14, s22, s2
	s_addc_u32 s15, s23, s3
	v_mov_b32_e32 v8, v210
	v_mov_b64_e32 v[2:3], s[14:15]
	v_ashrrev_i32_e32 v9, 6, v8
	v_and_b32_e32 v0, 63, v8
	s_movk_i32 s16, 0x2400
	v_mad_i64_i32 v[4:5], s[2:3], v9, s16, v[2:3]
	v_lshlrev_b32_e32 v0, 4, v0
	v_lshl_add_u64 v[4:5], v[4:5], 0, v[0:1]
	global_load_dwordx4 v[184:187], v[4:5], off
	v_lshlrev_b32_e32 v12, 2, v9
	v_lshlrev_b32_e32 v0, 10, v8
	v_and_b32_e32 v8, 15, v8
	v_lshlrev_b32_e32 v11, 8, v9
	v_bfe_u32 v9, v9, 2, 2
	v_and_b32_e32 v12, 12, v12
	v_and_b32_e32 v0, 0xc000, v0
	v_bitop3_b32 v8, v12, v8, v9 bitop3:0x36
	v_add_u32_e32 v0, s55, v0
	v_lshlrev_b32_e32 v8, 4, v8
	v_mov_b32_e32 v10, v210
	v_add3_u32 v232, v0, v8, v11
	v_mov_b32_e32 v9, v210
	v_mov_b32_e32 v14, v210
	s_movk_i32 s19, 0x1200
	s_movk_i32 s18, 0x200
	v_mov_b32_e32 v16, v208
	s_movk_i32 s20, 0x220
	v_mov_b32_e32 v17, v208
	v_mov_b32_e32 v18, v208
	v_mov_b32_e32 v19, v208
	v_mov_b32_e32 v20, v210
	v_mov_b32_e32 v21, v210
	s_mov_b32 s46, 0
	v_mov_b32_e32 v223, 0
	v_mov_b32_e32 v217, 0xf149f2ca
	s_nop 0
	v_add_u32_e32 v0, 0x200, v10
	v_and_b32_e32 v4, 63, v10
	v_ashrrev_i32_e32 v8, 6, v0
	v_lshlrev_b32_e32 v0, 4, v4
	v_mad_i64_i32 v[4:5], s[2:3], v8, s16, v[2:3]
	v_lshl_add_u64 v[4:5], v[4:5], 0, v[0:1]
	global_load_dwordx4 v[188:191], v[4:5], off
	v_lshlrev_b32_e32 v12, 2, v8
	v_lshlrev_b32_e32 v0, 10, v10
	v_and_b32_e32 v10, 15, v10
	v_lshlrev_b32_e32 v11, 8, v8
	v_bfe_u32 v8, v8, 2, 2
	v_and_b32_e32 v12, 12, v12
	v_and_b32_e32 v0, 0xc000, v0
	v_bitop3_b32 v8, v12, v10, v8 bitop3:0x36
	v_add_u32_e32 v0, s55, v0
	v_lshlrev_b32_e32 v8, 4, v8
	v_add3_u32 v233, v0, v8, v11
	v_mov_b32_e32 v10, v210
	s_nop 0
	v_add_u32_e32 v0, 0x400, v9
	v_and_b32_e32 v4, 63, v9
	v_ashrrev_i32_e32 v8, 6, v0
	v_lshlrev_b32_e32 v0, 4, v4
	v_mad_i64_i32 v[4:5], s[2:3], v8, s16, v[2:3]
	v_lshl_add_u64 v[4:5], v[4:5], 0, v[0:1]
	global_load_dwordx4 v[192:195], v[4:5], off
	v_lshlrev_b32_e32 v12, 2, v8
	v_lshlrev_b32_e32 v0, 10, v9
	v_and_b32_e32 v9, 15, v9
	v_lshlrev_b32_e32 v11, 8, v8
	v_bfe_u32 v8, v8, 2, 2
	v_and_b32_e32 v12, 12, v12
	v_and_b32_e32 v0, 0xc000, v0
	v_bitop3_b32 v8, v12, v9, v8 bitop3:0x36
	v_add_u32_e32 v0, s55, v0
	v_lshlrev_b32_e32 v8, 4, v8
	v_add3_u32 v234, v0, v8, v11
	v_mov_b32_e32 v9, v210
	s_nop 0
	v_add_u32_e32 v0, 0x600, v10
	v_and_b32_e32 v4, 63, v10
	v_ashrrev_i32_e32 v8, 6, v0
	v_lshlrev_b32_e32 v0, 4, v4
	v_mad_i64_i32 v[4:5], s[2:3], v8, s16, v[2:3]
	v_lshl_add_u64 v[4:5], v[4:5], 0, v[0:1]
	global_load_dwordx4 v[196:199], v[4:5], off
	v_lshlrev_b32_e32 v12, 2, v8
	v_lshlrev_b32_e32 v0, 10, v10
	v_and_b32_e32 v10, 15, v10
	v_lshlrev_b32_e32 v11, 8, v8
	v_bfe_u32 v8, v8, 2, 2
	v_and_b32_e32 v12, 12, v12
	v_and_b32_e32 v0, 0xc000, v0
	v_bitop3_b32 v8, v12, v10, v8 bitop3:0x36
	v_add_u32_e32 v0, s55, v0
	v_lshlrev_b32_e32 v8, 4, v8
	v_add3_u32 v235, v0, v8, v11
	v_mov_b32_e32 v10, v210
	s_nop 0
	v_add_u32_e32 v0, 0x800, v9
	v_and_b32_e32 v4, 63, v9
	v_ashrrev_i32_e32 v8, 6, v0
	v_lshlrev_b32_e32 v0, 4, v4
	v_mad_i64_i32 v[4:5], s[2:3], v8, s16, v[2:3]
	v_lshl_add_u64 v[4:5], v[4:5], 0, v[0:1]
	global_load_dwordx4 v[200:203], v[4:5], off
	v_lshlrev_b32_e32 v12, 2, v8
	v_lshlrev_b32_e32 v0, 10, v9
	v_and_b32_e32 v9, 15, v9
	v_lshlrev_b32_e32 v11, 8, v8
	v_bfe_u32 v8, v8, 2, 2
	v_and_b32_e32 v12, 12, v12
	v_and_b32_e32 v0, 0xc000, v0
	v_bitop3_b32 v8, v12, v9, v8 bitop3:0x36
	v_add_u32_e32 v0, s55, v0
	v_lshlrev_b32_e32 v8, 4, v8
	v_add3_u32 v236, v0, v8, v11
	v_mov_b32_e32 v9, v210
	s_nop 0
	v_add_u32_e32 v0, 0xa00, v10
	v_and_b32_e32 v4, 63, v10
	v_ashrrev_i32_e32 v8, 6, v0
	v_lshlrev_b32_e32 v0, 4, v4
	v_mad_i64_i32 v[4:5], s[2:3], v8, s16, v[2:3]
	v_lshl_add_u64 v[4:5], v[4:5], 0, v[0:1]
	global_load_dwordx4 v[204:207], v[4:5], off
	v_lshlrev_b32_e32 v12, 2, v8
	v_lshlrev_b32_e32 v0, 10, v10
	v_and_b32_e32 v10, 15, v10
	v_lshlrev_b32_e32 v11, 8, v8
	v_bfe_u32 v8, v8, 2, 2
	v_and_b32_e32 v12, 12, v12
	v_and_b32_e32 v0, 0xc000, v0
	v_bitop3_b32 v8, v12, v10, v8 bitop3:0x36
	v_add_u32_e32 v0, s55, v0
	v_lshlrev_b32_e32 v8, 4, v8
	v_add3_u32 v237, v0, v8, v11
	s_nop 0
	v_add_u32_e32 v0, 0xc00, v9
	v_and_b32_e32 v4, 63, v9
	v_ashrrev_i32_e32 v8, 6, v0
	v_lshlrev_b32_e32 v0, 4, v4
	v_mad_i64_i32 v[4:5], s[2:3], v8, s16, v[2:3]
	v_lshl_add_u64 v[4:5], v[4:5], 0, v[0:1]
	global_load_dwordx4 v[224:227], v[4:5], off
	v_lshlrev_b32_e32 v11, 2, v8
	v_lshlrev_b32_e32 v0, 10, v9
	v_and_b32_e32 v9, 15, v9
	v_lshlrev_b32_e32 v10, 8, v8
	v_bfe_u32 v8, v8, 2, 2
	v_and_b32_e32 v11, 12, v11
	v_and_b32_e32 v0, 0xc000, v0
	v_bitop3_b32 v8, v11, v9, v8 bitop3:0x36
	v_add_u32_e32 v0, s55, v0
	v_lshlrev_b32_e32 v8, 4, v8
	v_add3_u32 v238, v0, v8, v10
	v_mov_b32_e32 v8, v1
	v_mov_b32_e32 v9, v1
	s_waitcnt vmcnt(6)
	ds_write_b128 v232, v[184:187]
	s_waitcnt vmcnt(5)
	ds_write_b128 v233, v[188:191]
	s_waitcnt vmcnt(4)
	ds_write_b128 v234, v[192:195]
	s_waitcnt vmcnt(3)
	ds_write_b128 v235, v[196:199]
	s_waitcnt vmcnt(2)
	ds_write_b128 v236, v[200:203]
	s_waitcnt vmcnt(1)
	ds_write_b128 v237, v[204:207]
	s_waitcnt vmcnt(0)
; __device__ __forceinline__ int lau_v(int x) { asm volatile("" : "+v"(x)); return x; }
; #define AS_CV1(j_) do { if ((j_) < PAST / 64) { _Pragma("unroll") for (int i_ = 0; i_ < N1; ++i_) cv[i_] = AS_CVL(r1a[i_], r1b[i_]); } \
;     else { _Pragma("unroll") for (int i_ = 0; i_ < N1; ++i_) cv[i_] = AS_BC(r1a[i_]); } } while (0)
; __device__ __forceinline__ void unit(const bf16_t* __restrict__ Qs_bh  , const float* __restrict__ Clat  , const float* __restrict__ Ckpe  , const bf16_t* __restrict__ Kn  , ...
;     ...
;   for (int j = 0; j < 8; ++j) { const int c = lau_v(tid) + 512 * j, q = c >> 6, ch = c & 63;
;     *(bf16x8*)(lds + QIMG + (ch >> 4) * 16384 + off_b(q, ch & 15)) = *reinterpret_cast<const bf16x8*>(Qs_bh + (size_t)q * (HEADS * KVW) + ch * 8); }
;   bf16x8 qpe[2][2];
; #pragma unroll
;   for (int sb = 0; sb < 2; ++sb)
; #pragma unroll
;     for (int s2 = 0; s2 < 2; ++s2) { const int lq = lau_v(lane); qpe[sb][s2] = *reinterpret_cast<const bf16x8*>(Qs_bh + (unsigned)((32 * qh + 16 * sb + (lq & 15)) * (HEADS * KVW) + KVR + 32 * s2 + 8 * (lq >> 4))); }
;   int kb0, qb0, xsh, kpb[2];
;   { const int ln2 = lau_v(lane), l15b = ln2 & 15, g4b = ln2 >> 4; const int krow_ = 16 * cq + l15b, qrow_ = 32 * qh + l15b, clo = 16 * (g4b ^ ((l15b >> 2) & 3));
;     kb0 = KIMG + 256 * krow_ + clo; qb0 = QIMG + 256 * qrow_ + clo; xsh = (l15b & 3) << 6;
; #pragma unroll
;     for (int s = 0; s < 2; ++s) kpb[s] = KPE + krow_ * 128 + 16 * ((4 * s + g4b) ^ (krow_ & 7)); }
;   int vb[2], q4s;
;   { const int blk = (lane >> 4) & 1, q4 = (lane & 15) >> 2, p4 = lane & 3, c0 = 2 * blk + (p4 >> 1);
;     q4s = q4 << 6;
; #pragma unroll
;     for (int t = 0; t < 2; ++t) vb[t] = (int)(uintptr_t)lds + KIMG + cq * 16384 + 256 * (8 * hi + 4 * t + q4) + 16 * (c0 ^ ((2 * hi + t) & 3)) + 8 * (p4 & 1); }
;   const int sxw = SX + (32 * qh + l15) * SXLD + (16 * cq + 4 * g4) * 4;
;   const int sxr = SX + (32 * qh + r32) * SXLD + (8 * hi) * 4;
;   constexpr int NT = (PAST + DECS) / 64;
;   constexpr int N1 = 4, N2 = 8 - N1;
;   bf16x8 cv[9]; f32x4 r1a[N1], r1b[N1], r2a[N2 + 1], r2b[N2 + 1];
;     ...
;   float m_reg = -1e30f, l_reg = 0.f; f32x16 o[4] = {};
;   AS_LD1(0); AS_LD2(0); AS_CV1(0);
	ds_write_b128 v238, v[224:227]
	v_mov_b32_e32 v5, v1
	v_add_u32_e32 v0, 0xe00, v14
	v_and_b32_e32 v4, 63, v14
	v_ashrrev_i32_e32 v15, 6, v0
	v_lshlrev_b32_e32 v0, 4, v4
	v_mad_i64_i32 v[2:3], s[2:3], v15, s16, v[2:3]
	v_lshl_add_u64 v[2:3], v[2:3], 0, v[0:1]
	global_load_dwordx4 v[10:13], v[2:3], off
	v_lshlrev_b32_e32 v24, 2, v15
	v_lshlrev_b32_e32 v22, 10, v14
	v_and_b32_e32 v14, 15, v14
	v_lshlrev_b32_e32 v23, 8, v15
	v_bfe_u32 v15, v15, 2, 2
	v_and_b32_e32 v24, 12, v24
	v_and_b32_e32 v22, 0xc000, v22
	v_bitop3_b32 v14, v24, v14, v15 bitop3:0x36
	v_add_u32_e32 v22, s55, v22
	v_lshlrev_b32_e32 v14, 4, v14
	v_mov_b32_e32 v0, v208
	v_add3_u32 v14, v22, v14, v23
	s_lshl_b64 s[2:3], s[6:7], 12
	s_add_u32 s2, s2, s12
	s_addc_u32 s3, s3, s13
	s_lshl_b64 s[16:17], s[2:3], 11
	s_add_u32 s16, s8, s16
	s_addc_u32 s17, s9, s17
	s_lshl_b64 s[2:3], s[2:3], 8
	s_add_u32 s2, s10, s2
	s_addc_u32 s3, s11, s3
	s_add_u32 s0, s0, 0x4000
	s_addc_u32 s1, s1, 0
	v_mov_b32_e32 v2, v1
	v_mov_b32_e32 v3, v1
	v_mov_b32_e32 v4, v1
	v_mov_b32_e32 v6, v1
	v_mov_b32_e32 v7, v1
	s_waitcnt vmcnt(0)
	ds_write_b128 v14, v[10:13]
	s_nop 0
	v_and_or_b32 v10, v0, 15, s31
	v_ashrrev_i32_e32 v0, 1, v0
	v_mul_lo_u32 v10, v10, s19
	v_and_b32_e32 v0, -8, v0
	v_add3_u32 v0, v0, v10, s18
	v_lshl_add_u64 v[10:11], v[0:1], 1, s[14:15]
	global_load_dwordx4 v[80:83], v[10:11], off
	s_nop 0
	v_and_or_b32 v0, v16, 15, s31
	v_ashrrev_i32_e32 v10, 1, v16
	v_mul_lo_u32 v0, v0, s19
	v_and_b32_e32 v10, -8, v10
	v_add3_u32 v0, v10, v0, s20
	v_lshl_add_u64 v[10:11], v[0:1], 1, s[14:15]
	global_load_dwordx4 v[84:87], v[10:11], off
	s_nop 0
	v_and_or_b32 v0, v17, 15, s33
	v_ashrrev_i32_e32 v10, 1, v17
	v_mul_lo_u32 v0, v0, s19
	v_and_b32_e32 v10, -8, v10
	v_add3_u32 v0, v10, v0, s18
	v_lshl_add_u64 v[10:11], v[0:1], 1, s[14:15]
	global_load_dwordx4 v[88:91], v[10:11], off
	s_nop 0
	v_and_or_b32 v0, v18, 15, s33
	v_ashrrev_i32_e32 v10, 1, v18
	v_mul_lo_u32 v0, v0, s19
	v_and_b32_e32 v10, -8, v10
	v_add3_u32 v0, v10, v0, s20
	v_lshl_add_u64 v[10:11], v[0:1], 1, s[14:15]
	global_load_dwordx4 v[92:95], v[10:11], off
	s_movk_i32 s14, 0xffc0
	v_lshlrev_b32_e32 v0, 5, v20
	v_add_u32_e32 v12, 0x4000, v0
	v_add_u32_e32 v13, 0x8000, v0
	global_load_dwordx4 v[100:103], v0, s[16:17]
	global_load_dwordx4 v[96:99], v0, s[16:17] offset:16
	global_load_dwordx4 v[112:115], v12, s[16:17]
	global_load_dwordx4 v[108:111], v12, s[16:17] offset:16
	v_add_u32_e32 v0, 0xc000, v0
	global_load_dwordx4 v[140:143], v13, s[16:17]
	global_load_dwordx4 v[120:123], v13, s[16:17] offset:16
	global_load_dwordx4 v[152:155], v0, s[16:17]
	global_load_dwordx4 v[132:135], v0, s[16:17] offset:16
	v_lshrrev_b32_e32 v17, 2, v19
	v_lshlrev_b32_e32 v13, 5, v21
	v_add_u32_e32 v14, 0x10000, v13
	v_add_u32_e32 v15, 0x14000, v13
	v_add_u32_e32 v16, 0x18000, v13
	v_add_u32_e32 v13, 0x1c000, v13
	global_load_dwordx4 v[104:107], v14, s[16:17] offset:16
	global_load_dwordx4 v[164:167], v14, s[16:17]
	global_load_dwordx4 v[116:119], v15, s[16:17] offset:16
	global_load_dwordx4 v[168:171], v15, s[16:17]
	global_load_dwordx4 v[128:131], v16, s[16:17] offset:16
	global_load_dwordx4 v[172:175], v16, s[16:17]
	global_load_dwordx4 v[144:147], v13, s[16:17] offset:16
	global_load_dwordx4 v[176:179], v13, s[16:17]
	v_lshlrev_b32_e32 v12, 2, v21
	v_lshlrev_b32_e32 v0, 3, v21
	v_and_b32_e32 v12, 28, v12
	v_and_or_b32 v0, v0, s14, v12
	v_lshl_add_u64 v[12:13], v[0:1], 2, s[2:3]
	global_load_dwordx4 v[180:183], v[12:13], off
	global_load_dwordx4 v[156:159], v[12:13], off offset:128
	s_mul_hi_u32 s2, s0, 0x480
	s_mul_i32 s16, s1, 0x480
	s_mul_i32 s3, s0, 0x480
	s_add_i32 s2, s2, s16
	s_add_u32 s16, s24, s3
	v_and_b32_e32 v0, 15, v19
	v_ashrrev_i32_e32 v16, 4, v19
	s_addc_u32 s17, s25, s2
	s_lshl_b64 s[2:3], s[6:7], 23
	v_or_b32_e32 v20, s34, v0
	v_bitop3_b32 v17, v17, v16, 3 bitop3:0x6c
	v_bitop3_b32 v21, v16, v19, 7 bitop3:0x78
	v_add_u32_e32 v16, 4, v16
	s_add_u32 s47, s42, s2
	v_lshlrev_b32_e32 v18, 6, v19
	v_or_b32_e32 v0, s31, v0
	v_bitop3_b32 v16, v16, v19, 7 bitop3:0x78
	v_lshl_add_u32 v17, v17, 4, s55
	v_lshl_add_u32 v19, v20, 7, s55
	v_mov_b32_e32 v14, v1
	v_mov_b32_e32 v15, v1
	s_addc_u32 s48, s43, s3
	s_lshl_b64 s[2:3], s[6:7], 20
	v_and_b32_e32 v218, 0xc0, v18
	v_lshlrev_b32_e32 v18, 8, v20
	v_lshlrev_b32_e32 v21, 4, v21
	v_lshlrev_b32_e32 v16, 4, v16
	v_lshl_add_u32 v220, v0, 8, v17
	v_add_u32_e32 v0, 0x20000, v19
	v_mov_b32_e32 v10, v1
	v_mov_b32_e32 v11, v1
	v_mov_b32_e32 v12, v1
	v_mov_b32_e32 v13, v1
	s_add_u32 s18, s36, s2
	v_add3_u32 v219, v17, v18, s65
	v_add_u32_e32 v221, v0, v16
	v_add_u32_e32 v222, v0, v21
	v_mov_b32_e32 v0, v1
	v_mov_b64_e32 v[30:31], v[14:15]
	v_mov_b64_e32 v[46:47], v[14:15]
	v_mov_b64_e32 v[62:63], v[14:15]
	v_mov_b64_e32 v[78:79], v[14:15]
	s_mov_b64 s[14:15], 0
	s_addc_u32 s19, s37, s3
	v_mov_b64_e32 v[28:29], v[12:13]
	v_mov_b64_e32 v[26:27], v[10:11]
	v_mov_b64_e32 v[24:25], v[8:9]
	v_mov_b64_e32 v[22:23], v[6:7]
	v_mov_b64_e32 v[20:21], v[4:5]
	v_mov_b64_e32 v[18:19], v[2:3]
	v_mov_b64_e32 v[16:17], v[0:1]
	v_mov_b64_e32 v[44:45], v[12:13]
	v_mov_b64_e32 v[42:43], v[10:11]
	v_mov_b64_e32 v[40:41], v[8:9]
	v_mov_b64_e32 v[38:39], v[6:7]
	v_mov_b64_e32 v[36:37], v[4:5]
	v_mov_b64_e32 v[34:35], v[2:3]
	v_mov_b64_e32 v[32:33], v[0:1]
	v_mov_b64_e32 v[60:61], v[12:13]
	v_mov_b64_e32 v[58:59], v[10:11]
	s_waitcnt vmcnt(17)
	v_cvt_pk_bf16_f32 v124, v100, v101
	v_cvt_pk_bf16_f32 v125, v102, v103
	s_waitcnt vmcnt(16)
	v_cvt_pk_bf16_f32 v126, v96, v97
	v_cvt_pk_bf16_f32 v127, v98, v99
	s_waitcnt vmcnt(15)
	v_cvt_pk_bf16_f32 v136, v112, v113
	v_cvt_pk_bf16_f32 v137, v114, v115
	s_waitcnt vmcnt(14)
	v_cvt_pk_bf16_f32 v138, v108, v109
	v_cvt_pk_bf16_f32 v139, v110, v111
	s_waitcnt vmcnt(13)
	v_cvt_pk_bf16_f32 v148, v140, v141
	v_cvt_pk_bf16_f32 v149, v142, v143
	s_waitcnt vmcnt(12)
	v_cvt_pk_bf16_f32 v150, v120, v121
	v_cvt_pk_bf16_f32 v151, v122, v123
	s_waitcnt vmcnt(11)
	v_cvt_pk_bf16_f32 v160, v152, v153
	v_cvt_pk_bf16_f32 v161, v154, v155
	s_waitcnt vmcnt(10)
	v_cvt_pk_bf16_f32 v162, v132, v133
	v_cvt_pk_bf16_f32 v163, v134, v135
	v_mov_b64_e32 v[56:57], v[8:9]
	v_mov_b64_e32 v[54:55], v[6:7]
	v_mov_b64_e32 v[52:53], v[4:5]
	v_mov_b64_e32 v[50:51], v[2:3]
	v_mov_b64_e32 v[48:49], v[0:1]
	v_mov_b64_e32 v[76:77], v[12:13]
	v_mov_b64_e32 v[74:75], v[10:11]
	v_mov_b64_e32 v[72:73], v[8:9]
	v_mov_b64_e32 v[70:71], v[6:7]
	v_mov_b64_e32 v[68:69], v[4:5]
	v_mov_b64_e32 v[66:67], v[2:3]
	v_mov_b64_e32 v[64:65], v[0:1]
